# as v10 but the static priority raise goes to waves 0-3 instead of waves 4-7
# speedup vs baseline: 1.0207x; 1.0129x over previous
; #define PG8_STAGE(bufoff, gbase, voff) do { _Pragma("unroll") for (int _i = 0; _i < 2; ++_i) \
;         __builtin_amdgcn_global_load_lds((const unsigned*)((const char*)(gbase) + (voff)[_i]), (LAS unsigned*)(lds + (bufoff) + ldsw + _i * 8192), 16, 0, 0); } while (0)
; #define PG8_WAIT_V(n) asm volatile("s_waitcnt vmcnt(" #n ")" ::: "memory")
; #define PG8_BAR __builtin_amdgcn_s_barrier()
; template <class Epi, class Sched>
; __device__ __forceinline__ void gemm_phase(LAS unsigned char* lds, const Gemm g, const Sched& S, const Epi& E) {
;     ...
;     const int wid = __builtin_amdgcn_readfirstlane(tid >> 6), lane = tid & 63, wr = wid >> 2, wc = wid & 3, fr = lane & 15, fq = lane >> 4;
;     const int K = g.K;
;     unsigned voffA[2], voffB[2];
; #pragma unroll
;     for (int i = 0; i < 2; ++i) { int R, C; stage_rc(tid * 16 + i * 8192, R, C); const int Rb = Epi::PERM ? ((R & ~31) + perm32(R & 31)) : R;
;         voffA[i] = (unsigned)(R * K + C) * 2u; voffB[i] = (unsigned)(Rb * K + C) * 2u; }
;     const size_t kstep = (size_t)(BK * 2);
;     const size_t hstep = (size_t)HALF * K * 2;
;     const size_t tstep = 2 * hstep;
;     const unsigned ldsw = (unsigned)wid * 1024u;
;     const int aoff = lds_byte(wr * 64 + fr, fq * 8), boff = lds_byte(wc * 32 + fr, fq * 8);
;     ...
;     Unit cur, nxt; int ui = 0;
;     if (!S.next(0, cur)) return;
;     f32x4 acc[2][2][4][2];
; #pragma unroll
;     for (int a = 0; a < 2; ++a)
; #pragma unroll
;         for (int b = 0; b < 2; ++b)
; #pragma unroll
;             for (int m = 0; m < 4; ++m)
; #pragma unroll
;                 for (int n = 0; n < 2; ++n) acc[a][b][m][n] = (f32x4){0.f, 0.f, 0.f, 0.f};
;     bf16x8 At[4][2], B0[2][2], B1[2][2];
;     const char* cA = (const char*)g.A + (size_t)cur.pm * tstep + (size_t)cur.kt0 * kstep; const char* cB = (const char*)g.Bt + (size_t)cur.pn * tstep + (size_t)cur.kt0 * kstep;
;     PG8_STAGE(PG8_SB(0, 0), cB, voffB); PG8_STAGE(PG8_SA(0, 0), cA, voffA); PG8_STAGE(PG8_SB(0, 1), cB + hstep, voffB); PG8_STAGE(PG8_SA(0, 1), cA + hstep, voffA);
;     if (wr == 1) PG8_BAR;
;     PG8_WAIT_V(4); PG8_BAR;
.LBB0_110:
	v_readlane_b32 s2, v253, 14
	s_mulk_i32 s2, 0x2100
	s_add_i32 s26, s2, 0
	s_and_b64 vcc, exec, s[0:1]
	s_cbranch_vccz .LBB0_134
	v_readlane_b32 s0, v253, 27
	s_cmp_gt_i32 s0, 1
	s_cbranch_scc0 .LBB0_135
	s_cmp_gt_i32 s0, 2
	s_mov_b64 s[10:11], 0
	s_cbranch_scc0 .LBB0_136
	s_cmp_gt_i32 s0, 3
	s_cbranch_scc0 .LBB0_149
	v_readlane_b32 s0, v251, 11
	v_mov_b32_e32 v14, v178
	v_readlane_b32 s1, v251, 12
	s_andn2_b64 vcc, exec, s[0:1]
	v_readfirstlane_b32 s24, v14
	s_cbranch_vccnz .LBB0_130
	v_lshlrev_b32_e32 v0, 4, v14
	v_add_u32_e32 v1, 0x2000, v0
	v_ashrrev_i32_e32 v2, 31, v1
	v_lshrrev_b32_e32 v2, 22, v2
	v_add_u32_e32 v2, v1, v2
	v_ashrrev_i32_e32 v8, 10, v2
	v_mul_i32_i24_e32 v2, 0x400, v8
	v_sub_u32_e32 v1, v1, v2
	v_lshrrev_b32_e32 v2, 4, v1
	v_bitop3_b32 v1, v2, v1, 32 bitop3:0x6c
	v_ashrrev_i32_e32 v2, 31, v1
	v_lshrrev_b32_e32 v2, 26, v2
	v_add_u32_e32 v2, v1, v2
	v_lshlrev_b32_e32 v3, 3, v8
	v_ashrrev_i32_e32 v9, 6, v2
	v_and_b32_e32 v3, -16, v3
	v_add_u32_e32 v3, v9, v3
	v_and_b32_e32 v4, 3, v9
	s_mov_b32 s2, 0xfffe0
	v_lshrrev_b32_e32 v5, 2, v3
	v_lshlrev_b32_e32 v6, 1, v3
	v_and_b32_e32 v2, 0xc0, v2
	v_and_or_b32 v4, v3, s2, v4
	v_and_b32_e32 v5, 4, v5
	v_and_b32_e32 v6, 24, v6
	v_sub_u32_e32 v1, v1, v2
	v_or3_b32 v4, v4, v5, v6
	v_lshlrev_b32_e32 v5, 5, v8
	v_ashrrev_i16_sdwa v1, v183, sext(v1) dst_sel:DWORD dst_unused:UNUSED_PAD src0_sel:DWORD src1_sel:BYTE_0
	v_and_b32_e32 v5, 32, v5
	v_bfe_i32 v10, v1, 0, 16
	v_add_lshl_u32 v1, v5, v10, 1
	v_lshl_add_u32 v128, v4, 12, v1
	v_lshl_add_u32 v130, v3, 12, v1
	v_bfe_i32 v1, v14, 27, 1
	v_lshrrev_b32_e32 v1, 22, v1
	v_add_u32_e32 v1, v0, v1
	v_and_b32_e32 v1, 0xfffffc00, v1
	v_sub_u32_e32 v0, v0, v1
	v_lshrrev_b32_e32 v1, 4, v0
	v_ashrrev_i32_e32 v2, 31, v14
	v_bitop3_b32 v0, v1, v0, 32 bitop3:0x6c
	v_lshrrev_b32_e32 v2, 26, v2
	v_ashrrev_i32_e32 v1, 31, v0
	v_add_u32_e32 v2, v14, v2
	v_lshrrev_b32_e32 v1, 26, v1
	v_ashrrev_i32_e32 v12, 6, v2
	v_add_u32_e32 v1, v0, v1
	v_lshlrev_b32_e32 v2, 3, v12
	v_ashrrev_i32_e32 v11, 6, v1
	v_and_b32_e32 v2, -16, v2
	v_add_u32_e32 v2, v11, v2
	s_add_u32 s25, s62, 0x8400000
	v_and_b32_e32 v3, 3, v11
	v_lshrrev_b32_e32 v4, 2, v2
	v_lshlrev_b32_e32 v5, 1, v2
	v_and_b32_e32 v1, 0xc0, v1
	s_addc_u32 s27, s63, 0
	s_ashr_i32 s0, s24, 6
	v_and_or_b32 v3, v2, s2, v3
	v_and_b32_e32 v4, 4, v4
	v_and_b32_e32 v5, 24, v5
	v_sub_u32_e32 v0, v0, v1
	s_ashr_i32 s1, s24, 8
	s_lshl_b32 s29, s0, 10
	v_or3_b32 v3, v3, v4, v5
	v_lshlrev_b32_e32 v4, 5, v12
	v_ashrrev_i16_sdwa v0, v183, sext(v0) dst_sel:DWORD dst_unused:UNUSED_PAD src0_sel:DWORD src1_sel:BYTE_0
	v_readlane_b32 s2, v252, 36
	v_and_b32_e32 v4, 32, v4
	v_bfe_i32 v13, v0, 0, 16
	v_readlane_b32 s3, v252, 37
	s_add_u32 s20, s25, s2
	v_add_lshl_u32 v0, v4, v13, 1
	s_addc_u32 s21, s27, s3
	s_add_i32 s30, s29, 0
	v_lshl_add_u32 v148, v3, 12, v0
	s_add_i32 m0, s30, 0x10000
	v_readlane_b32 s2, v252, 40
	global_load_lds_dwordx4 v148, s[20:21]
	s_add_i32 m0, s30, 0x12000
	v_readlane_b32 s4, v253, 15
	v_readlane_b32 s3, v252, 41
	s_add_u32 s16, s4, s2
	v_readlane_b32 s2, v253, 16
	v_lshl_add_u32 v132, v2, 12, v0
	global_load_lds_dwordx4 v128, s[20:21]
	s_addc_u32 s17, s2, s3
	s_mov_b32 m0, s30
	s_add_i32 s31, s30, 0x2000
	global_load_lds_dwordx4 v132, s[16:17]
	s_mov_b32 m0, s31
	s_add_u32 s2, s20, 0x80000
	global_load_lds_dwordx4 v130, s[16:17]
	s_addc_u32 s3, s21, 0
	s_add_i32 m0, s30, 0x14000
	v_mov_b32_e32 v129, v149
	global_load_lds_dwordx4 v148, s[2:3]
	s_add_i32 m0, s30, 0x16000
	v_mov_b32_e32 v133, v149
	global_load_lds_dwordx4 v128, s[2:3]
	s_add_u32 s2, s16, 0x80000
	s_addc_u32 s3, s17, 0
	s_add_i32 s33, s30, 0x4000
	s_mov_b32 m0, s33
	s_add_i32 s34, s30, 0x6000
	global_load_lds_dwordx4 v132, s[2:3]
	s_mov_b32 m0, s34
	v_mov_b32_e32 v131, v149
	global_load_lds_dwordx4 v130, s[2:3]
	v_lshl_add_u64 v[6:7], s[20:21], 0, v[148:149]
	v_lshl_add_u64 v[4:5], s[20:21], 0, v[128:129]
	v_lshl_add_u64 v[2:3], s[16:17], 0, v[132:133]
	s_cmp_lg_u32 s1, 1
	v_lshl_add_u64 v[0:1], s[16:17], 0, v[130:131]
	s_setprio 1
	s_cbranch_scc1 .LBB0_117
	s_barrier
	s_setprio 0

; #define PG8_STAGE(bufoff, gbase, voff) do { _Pragma("unroll") for (int _i = 0; _i < 2; ++_i) \
;         __builtin_amdgcn_global_load_lds((const unsigned*)((const char*)(gbase) + (voff)[_i]), (LAS unsigned*)(lds + (bufoff) + ldsw + _i * 8192), 16, 0, 0); } while (0)
; #define PG8_WAIT_V(n) asm volatile("s_waitcnt vmcnt(" #n ")" ::: "memory")
; #define PG8_BAR __builtin_amdgcn_s_barrier()
; template <class Epi, class Sched>
; __device__ __forceinline__ void gemm_phase(LAS unsigned char* lds, const Gemm g, const Sched& S, const Epi& E) {
;     ...
;     const int wid = __builtin_amdgcn_readfirstlane(tid >> 6), lane = tid & 63, wr = wid >> 2, wc = wid & 3, fr = lane & 15, fq = lane >> 4;
;     const int K = g.K;
;     unsigned voffA[2], voffB[2];
; #pragma unroll
;     for (int i = 0; i < 2; ++i) { int R, C; stage_rc(tid * 16 + i * 8192, R, C); const int Rb = Epi::PERM ? ((R & ~31) + perm32(R & 31)) : R;
;         voffA[i] = (unsigned)(R * K + C) * 2u; voffB[i] = (unsigned)(Rb * K + C) * 2u; }
;     const size_t kstep = (size_t)(BK * 2);
;     const size_t hstep = (size_t)HALF * K * 2;
;     const size_t tstep = 2 * hstep;
;     const unsigned ldsw = (unsigned)wid * 1024u;
;     const int aoff = lds_byte(wr * 64 + fr, fq * 8), boff = lds_byte(wc * 32 + fr, fq * 8);
;     ...
;     Unit cur, nxt; int ui = 0;
;     if (!S.next(0, cur)) return;
;     f32x4 acc[2][2][4][2];
; #pragma unroll
;     for (int a = 0; a < 2; ++a)
; #pragma unroll
;         for (int b = 0; b < 2; ++b)
; #pragma unroll
;             for (int m = 0; m < 4; ++m)
; #pragma unroll
;                 for (int n = 0; n < 2; ++n) acc[a][b][m][n] = (f32x4){0.f, 0.f, 0.f, 0.f};
;     bf16x8 At[4][2], B0[2][2], B1[2][2];
;     const char* cA = (const char*)g.A + (size_t)cur.pm * tstep + (size_t)cur.kt0 * kstep; const char* cB = (const char*)g.Bt + (size_t)cur.pn * tstep + (size_t)cur.kt0 * kstep;
;     PG8_STAGE(PG8_SB(0, 0), cB, voffB); PG8_STAGE(PG8_SA(0, 0), cA, voffA); PG8_STAGE(PG8_SB(0, 1), cB + hstep, voffB); PG8_STAGE(PG8_SA(0, 1), cA + hstep, voffA);
;     if (wr == 1) PG8_BAR;
;     PG8_WAIT_V(4); PG8_BAR;
.LBB0_154:
	v_readlane_b32 s0, v251, 15
	v_mov_b32_e32 v16, v178
	v_readlane_b32 s1, v251, 16
	s_andn2_b64 vcc, exec, s[0:1]
	v_readfirstlane_b32 s27, v16
	s_cbranch_vccnz .LBB0_178
	v_lshlrev_b32_e32 v0, 4, v16
	v_add_u32_e32 v1, 0x2000, v0
	v_ashrrev_i32_e32 v2, 31, v1
	v_lshrrev_b32_e32 v2, 22, v2
	v_add_u32_e32 v2, v1, v2
	v_ashrrev_i32_e32 v8, 10, v2
	v_mul_i32_i24_e32 v2, 0x400, v8
	v_sub_u32_e32 v1, v1, v2
	v_lshrrev_b32_e32 v2, 4, v1
	v_bitop3_b32 v1, v2, v1, 32 bitop3:0x6c
	v_ashrrev_i32_e32 v2, 31, v1
	v_lshrrev_b32_e32 v2, 26, v2
	v_add_u32_e32 v2, v1, v2
	v_ashrrev_i32_e32 v9, 6, v2
	v_and_b32_e32 v2, 0xc0, v2
	v_sub_u32_e32 v1, v1, v2
	v_ashrrev_i16_sdwa v1, v183, sext(v1) dst_sel:DWORD dst_unused:UNUSED_PAD src0_sel:DWORD src1_sel:BYTE_0
	v_bfe_i32 v11, v1, 0, 16
	v_bfe_i32 v1, v16, 27, 1
	v_lshrrev_b32_e32 v1, 22, v1
	v_add_u32_e32 v1, v0, v1
	v_and_b32_e32 v1, 0xfffffc00, v1
	v_sub_u32_e32 v0, v0, v1
	s_ashr_i32 s0, s27, 6
	v_lshrrev_b32_e32 v1, 4, v0
	v_ashrrev_i32_e32 v2, 31, v16
	s_ashr_i32 s1, s27, 8
	s_lshl_b32 s29, s0, 10
	v_bitop3_b32 v0, v1, v0, 32 bitop3:0x6c
	v_lshrrev_b32_e32 v2, 26, v2
	s_add_u32 s30, s62, 0xb800000
	v_ashrrev_i32_e32 v1, 31, v0
	v_add_u32_e32 v2, v16, v2
	s_addc_u32 s31, s63, 0
	v_readlane_b32 s4, v253, 27
	v_lshrrev_b32_e32 v1, 26, v1
	v_ashrrev_i32_e32 v13, 6, v2
	s_cmp_eq_u32 s4, 10
	s_mov_b32 s4, 0x6e00000
	v_lshlrev_b32_e32 v3, 3, v8
	v_add_u32_e32 v1, v0, v1
	v_lshlrev_b32_e32 v2, 3, v13
	s_cselect_b32 s4, s4, 0x5800000
	v_and_b32_e32 v3, 0x7ffff0, v3
	v_ashrrev_i32_e32 v12, 6, v1
	v_and_b32_e32 v2, 0x7ffff0, v2
	s_add_u32 s33, s62, s4
	v_add_u32_e32 v3, v9, v3
	s_movk_i32 s4, 0x1600
	v_add_u32_e32 v2, v12, v2
	v_mul_lo_u32 v3, v3, s4
	v_mul_lo_u32 v2, v2, s4
	v_readlane_b32 s4, v252, 28
	s_addc_u32 s34, s63, 0
	v_readlane_b32 s5, v252, 29
	s_mov_b32 s6, s4
	s_mul_i32 s4, s4, 0x2c0000
	v_lshlrev_b32_e32 v4, 5, v8
	s_add_u32 s4, s30, s4
	s_mul_hi_i32 s5, s6, 0x2c0000
	v_and_b32_e32 v10, 32, v4
	s_addc_u32 s5, s31, s5
	v_readlane_b32 s6, v252, 26
	v_or_b32_e32 v3, v3, v10
	v_and_b32_e32 v1, 0xc0, v1
	s_add_u32 s6, s33, s6
	v_readlane_b32 s7, v252, 27
	v_add_lshl_u32 v140, v3, v11, 1
	v_lshlrev_b32_e32 v3, 5, v13
	v_sub_u32_e32 v0, v0, v1
	s_addc_u32 s7, s34, s7
	v_readlane_b32 s14, v251, 17
	v_and_b32_e32 v14, 32, v3
	v_ashrrev_i16_sdwa v0, v183, sext(v0) dst_sel:DWORD dst_unused:UNUSED_PAD src0_sel:DWORD src1_sel:BYTE_0
	v_readlane_b32 s15, v251, 18
	s_add_u32 s20, s6, s14
	v_or_b32_e32 v2, v2, v14
	v_bfe_i32 v15, v0, 0, 16
	s_addc_u32 s21, s7, s15
	s_add_i32 s35, s29, 0
	v_add_lshl_u32 v148, v2, v15, 1
	s_add_i32 m0, s35, 0x10000
	v_mov_b32_e32 v141, v149
	global_load_lds_dwordx4 v148, s[20:21]
	s_add_i32 m0, s35, 0x12000
	s_add_u32 s16, s4, s14
	global_load_lds_dwordx4 v140, s[20:21]
	s_addc_u32 s17, s5, s15
	s_mov_b32 m0, s35
	s_add_i32 s36, s35, 0x2000
	global_load_lds_dwordx4 v148, s[16:17]
	s_mov_b32 m0, s36
	s_add_u32 s4, s20, 0x160000
	global_load_lds_dwordx4 v140, s[16:17]
	s_addc_u32 s5, s21, 0
	s_add_i32 m0, s35, 0x14000
	v_lshl_add_u64 v[6:7], s[20:21], 0, v[148:149]
	global_load_lds_dwordx4 v148, s[4:5]
	s_add_i32 m0, s35, 0x16000
	v_lshl_add_u64 v[4:5], s[20:21], 0, v[140:141]
	global_load_lds_dwordx4 v140, s[4:5]
	s_add_u32 s4, s16, 0x160000
	s_addc_u32 s5, s17, 0
	s_add_i32 s37, s35, 0x4000
	s_mov_b32 m0, s37
	s_add_i32 s38, s35, 0x6000
	global_load_lds_dwordx4 v148, s[4:5]
	s_mov_b32 m0, s38
	v_lshl_add_u64 v[2:3], s[16:17], 0, v[148:149]
	global_load_lds_dwordx4 v140, s[4:5]
	s_cmp_lg_u32 s1, 1
	v_lshl_add_u64 v[0:1], s[16:17], 0, v[140:141]
	s_setprio 1
	s_cbranch_scc1 .LBB0_157
	s_barrier
	s_setprio 0

; #define PG8_STAGE(bufoff, gbase, voff) do { _Pragma("unroll") for (int _i = 0; _i < 2; ++_i) \
;         __builtin_amdgcn_global_load_lds((const unsigned*)((const char*)(gbase) + (voff)[_i]), (LAS unsigned*)(lds + (bufoff) + ldsw + _i * 8192), 16, 0, 0); } while (0)
; #define PG8_WAIT_V(n) asm volatile("s_waitcnt vmcnt(" #n ")" ::: "memory")
; #define PG8_BAR __builtin_amdgcn_s_barrier()
; template <class Epi, class Sched>
; __device__ __forceinline__ void gemm_phase(LAS unsigned char* lds, const Gemm g, const Sched& S, const Epi& E) {
;     ...
;     const int wid = __builtin_amdgcn_readfirstlane(tid >> 6), lane = tid & 63, wr = wid >> 2, wc = wid & 3, fr = lane & 15, fq = lane >> 4;
;     const int K = g.K;
;     unsigned voffA[2], voffB[2];
; #pragma unroll
;     for (int i = 0; i < 2; ++i) { int R, C; stage_rc(tid * 16 + i * 8192, R, C); const int Rb = Epi::PERM ? ((R & ~31) + perm32(R & 31)) : R;
;         voffA[i] = (unsigned)(R * K + C) * 2u; voffB[i] = (unsigned)(Rb * K + C) * 2u; }
;     const size_t kstep = (size_t)(BK * 2);
;     const size_t hstep = (size_t)HALF * K * 2;
;     const size_t tstep = 2 * hstep;
;     const unsigned ldsw = (unsigned)wid * 1024u;
;     const int aoff = lds_byte(wr * 64 + fr, fq * 8), boff = lds_byte(wc * 32 + fr, fq * 8);
;     ...
;     Unit cur, nxt; int ui = 0;
;     if (!S.next(0, cur)) return;
;     f32x4 acc[2][2][4][2];
; #pragma unroll
;     for (int a = 0; a < 2; ++a)
; #pragma unroll
;         for (int b = 0; b < 2; ++b)
; #pragma unroll
;             for (int m = 0; m < 4; ++m)
; #pragma unroll
;                 for (int n = 0; n < 2; ++n) acc[a][b][m][n] = (f32x4){0.f, 0.f, 0.f, 0.f};
;     bf16x8 At[4][2], B0[2][2], B1[2][2];
;     const char* cA = (const char*)g.A + (size_t)cur.pm * tstep + (size_t)cur.kt0 * kstep; const char* cB = (const char*)g.Bt + (size_t)cur.pn * tstep + (size_t)cur.kt0 * kstep;
;     PG8_STAGE(PG8_SB(0, 0), cB, voffB); PG8_STAGE(PG8_SA(0, 0), cA, voffA); PG8_STAGE(PG8_SB(0, 1), cB + hstep, voffB); PG8_STAGE(PG8_SA(0, 1), cA + hstep, voffA);
;     if (wr == 1) PG8_BAR;
;     PG8_WAIT_V(4); PG8_BAR;
.LBB0_205:
	s_nop 0
	v_readlane_b32 s4, v253, 23
	v_readlane_b32 s5, v253, 24
	s_andn2_b64 vcc, exec, s[4:5]
	s_cbranch_vccnz .LBB0_248
	v_readlane_b32 s0, v251, 20
	v_mov_b32_e32 v8, v178
	v_readlane_b32 s1, v251, 21
	s_andn2_b64 vcc, exec, s[0:1]
	v_readfirstlane_b32 s24, v8
	s_cbranch_vccnz .LBB0_218
	v_lshlrev_b32_e32 v0, 4, v8
	v_add_u32_e32 v1, 0x2000, v0
	v_ashrrev_i32_e32 v2, 31, v1
	v_lshrrev_b32_e32 v2, 22, v2
	v_add_u32_e32 v2, v1, v2
	v_ashrrev_i32_e32 v9, 10, v2
	v_mul_i32_i24_e32 v2, 0x400, v9
	v_sub_u32_e32 v1, v1, v2
	v_lshrrev_b32_e32 v2, 4, v1
	v_bitop3_b32 v1, v2, v1, 32 bitop3:0x6c
	v_ashrrev_i32_e32 v2, 31, v1
	v_lshrrev_b32_e32 v2, 26, v2
	v_add_u32_e32 v2, v1, v2
	v_lshlrev_b32_e32 v3, 3, v9
	v_ashrrev_i32_e32 v10, 6, v2
	v_and_b32_e32 v3, -16, v3
	v_add_u32_e32 v3, v10, v3
	v_and_b32_e32 v4, 3, v10
	s_mov_b32 s4, 0xfffe0
	v_lshrrev_b32_e32 v5, 2, v3
	v_lshlrev_b32_e32 v6, 1, v3
	v_and_b32_e32 v2, 0xc0, v2
	v_and_or_b32 v4, v3, s4, v4
	v_and_b32_e32 v5, 4, v5
	v_and_b32_e32 v6, 24, v6
	v_sub_u32_e32 v1, v1, v2
	v_or3_b32 v4, v4, v5, v6
	v_lshlrev_b32_e32 v5, 5, v9
	v_ashrrev_i16_sdwa v1, v183, sext(v1) dst_sel:DWORD dst_unused:UNUSED_PAD src0_sel:DWORD src1_sel:BYTE_0
	v_and_b32_e32 v5, 32, v5
	v_bfe_i32 v11, v1, 0, 16
	v_add_lshl_u32 v1, v5, v11, 1
	v_lshl_add_u32 v128, v4, 12, v1
	v_lshl_add_u32 v130, v3, 12, v1
	v_bfe_i32 v1, v8, 27, 1
	v_lshrrev_b32_e32 v1, 22, v1
	v_add_u32_e32 v1, v0, v1
	v_and_b32_e32 v1, 0xfffffc00, v1
	v_sub_u32_e32 v0, v0, v1
	v_lshrrev_b32_e32 v1, 4, v0
	v_ashrrev_i32_e32 v2, 31, v8
	v_bitop3_b32 v0, v1, v0, 32 bitop3:0x6c
	v_lshrrev_b32_e32 v2, 26, v2
	v_ashrrev_i32_e32 v1, 31, v0
	v_add_u32_e32 v2, v8, v2
	v_lshrrev_b32_e32 v1, 26, v1
	v_ashrrev_i32_e32 v13, 6, v2
	v_readlane_b32 s0, v253, 27
	v_add_u32_e32 v1, v0, v1
	v_lshlrev_b32_e32 v2, 3, v13
	s_cmp_eq_u32 s0, 9
	v_ashrrev_i32_e32 v12, 6, v1
	v_and_b32_e32 v2, -16, v2
	s_cselect_b32 s0, 0x2c00000, 0
	v_add_u32_e32 v2, v12, v2
	s_add_u32 s25, s62, s0
	v_and_b32_e32 v3, 3, v12
	v_lshrrev_b32_e32 v4, 2, v2
	v_lshlrev_b32_e32 v5, 1, v2
	v_and_b32_e32 v1, 0xc0, v1
	s_addc_u32 s27, s63, 0
	s_ashr_i32 s1, s24, 6
	v_and_or_b32 v3, v2, s4, v3
	v_and_b32_e32 v4, 4, v4
	v_and_b32_e32 v5, 24, v5
	v_sub_u32_e32 v0, v0, v1
	s_ashr_i32 s0, s24, 8
	s_lshl_b32 s29, s1, 10
	v_or3_b32 v3, v3, v4, v5
	v_lshlrev_b32_e32 v4, 5, v13
	v_ashrrev_i16_sdwa v0, v183, sext(v0) dst_sel:DWORD dst_unused:UNUSED_PAD src0_sel:DWORD src1_sel:BYTE_0
	v_readlane_b32 s4, v252, 47
	v_and_b32_e32 v4, 32, v4
	v_bfe_i32 v14, v0, 0, 16
	v_readlane_b32 s5, v252, 48
	s_add_u32 s20, s25, s4
	v_add_lshl_u32 v0, v4, v14, 1
	s_addc_u32 s21, s27, s5
	s_add_i32 s30, s29, 0
	v_lshl_add_u32 v148, v3, 12, v0
	s_add_i32 m0, s30, 0x10000
	v_readlane_b32 s4, v252, 58
	global_load_lds_dwordx4 v148, s[20:21]
	s_add_i32 m0, s30, 0x12000
	v_readlane_b32 s6, v253, 15
	v_readlane_b32 s5, v252, 59
	s_add_u32 s16, s6, s4
	v_readlane_b32 s4, v253, 16
	v_lshl_add_u32 v132, v2, 12, v0
	global_load_lds_dwordx4 v128, s[20:21]
	s_addc_u32 s17, s4, s5
	s_mov_b32 m0, s30
	s_add_i32 s31, s30, 0x2000
	global_load_lds_dwordx4 v132, s[16:17]
	s_mov_b32 m0, s31
	s_add_u32 s4, s20, 0x80000
	global_load_lds_dwordx4 v130, s[16:17]
	s_addc_u32 s5, s21, 0
	s_add_i32 m0, s30, 0x14000
	v_mov_b32_e32 v129, v149
	global_load_lds_dwordx4 v148, s[4:5]
	s_add_i32 m0, s30, 0x16000
	v_mov_b32_e32 v133, v149
	global_load_lds_dwordx4 v128, s[4:5]
	s_add_u32 s4, s16, 0x80000
	s_addc_u32 s5, s17, 0
	s_add_i32 s33, s30, 0x4000
	s_mov_b32 m0, s33
	s_add_i32 s34, s30, 0x6000
	global_load_lds_dwordx4 v132, s[4:5]
	s_mov_b32 m0, s34
	v_mov_b32_e32 v131, v149
	global_load_lds_dwordx4 v130, s[4:5]
	v_lshl_add_u64 v[6:7], s[20:21], 0, v[148:149]
	v_lshl_add_u64 v[4:5], s[20:21], 0, v[128:129]
	v_lshl_add_u64 v[2:3], s[16:17], 0, v[132:133]
	s_cmp_lg_u32 s0, 1
	v_lshl_add_u64 v[0:1], s[16:17], 0, v[130:131]
	s_setprio 1
	s_cbranch_scc1 .LBB0_209
	s_barrier
	s_setprio 0

; #define PG8_STAGE(bufoff, gbase, voff) do { _Pragma("unroll") for (int _i = 0; _i < 2; ++_i) \
;         __builtin_amdgcn_global_load_lds((const unsigned*)((const char*)(gbase) + (voff)[_i]), (LAS unsigned*)(lds + (bufoff) + ldsw + _i * 8192), 16, 0, 0); } while (0)
; #define PG8_WAIT_V(n) asm volatile("s_waitcnt vmcnt(" #n ")" ::: "memory")
; #define PG8_BAR __builtin_amdgcn_s_barrier()
; template <class Epi, class Sched>
; __device__ __forceinline__ void gemm_phase(LAS unsigned char* lds, const Gemm g, const Sched& S, const Epi& E) {
;     ...
;     const int wid = __builtin_amdgcn_readfirstlane(tid >> 6), lane = tid & 63, wr = wid >> 2, wc = wid & 3, fr = lane & 15, fq = lane >> 4;
;     const int K = g.K;
;     unsigned voffA[2], voffB[2];
; #pragma unroll
;     for (int i = 0; i < 2; ++i) { int R, C; stage_rc(tid * 16 + i * 8192, R, C); const int Rb = Epi::PERM ? ((R & ~31) + perm32(R & 31)) : R;
;         voffA[i] = (unsigned)(R * K + C) * 2u; voffB[i] = (unsigned)(Rb * K + C) * 2u; }
;     const size_t kstep = (size_t)(BK * 2);
;     const size_t hstep = (size_t)HALF * K * 2;
;     const size_t tstep = 2 * hstep;
;     const unsigned ldsw = (unsigned)wid * 1024u;
;     const int aoff = lds_byte(wr * 64 + fr, fq * 8), boff = lds_byte(wc * 32 + fr, fq * 8);
;     ...
;     Unit cur, nxt; int ui = 0;
;     if (!S.next(0, cur)) return;
;     f32x4 acc[2][2][4][2];
; #pragma unroll
;     for (int a = 0; a < 2; ++a)
; #pragma unroll
;         for (int b = 0; b < 2; ++b)
; #pragma unroll
;             for (int m = 0; m < 4; ++m)
; #pragma unroll
;                 for (int n = 0; n < 2; ++n) acc[a][b][m][n] = (f32x4){0.f, 0.f, 0.f, 0.f};
;     bf16x8 At[4][2], B0[2][2], B1[2][2];
;     const char* cA = (const char*)g.A + (size_t)cur.pm * tstep + (size_t)cur.kt0 * kstep; const char* cB = (const char*)g.Bt + (size_t)cur.pn * tstep + (size_t)cur.kt0 * kstep;
;     PG8_STAGE(PG8_SB(0, 0), cB, voffB); PG8_STAGE(PG8_SA(0, 0), cA, voffA); PG8_STAGE(PG8_SB(0, 1), cB + hstep, voffB); PG8_STAGE(PG8_SA(0, 1), cA + hstep, voffA);
;     if (wr == 1) PG8_BAR;
;     PG8_WAIT_V(4); PG8_BAR;
.LBB0_250:
	s_nop 0
	v_readlane_b32 s0, v253, 21
	v_readlane_b32 s1, v253, 22
	s_andn2_b64 vcc, exec, s[0:1]
	s_cbranch_vccnz .LBB0_272
	v_readlane_b32 s0, v251, 15
	v_mov_b32_e32 v16, v178
	v_readlane_b32 s1, v251, 16
	s_andn2_b64 vcc, exec, s[0:1]
	v_readfirstlane_b32 s27, v16
	s_cbranch_vccnz .LBB0_276
	v_lshlrev_b32_e32 v0, 4, v16
	v_add_u32_e32 v1, 0x2000, v0
	v_ashrrev_i32_e32 v2, 31, v1
	v_lshrrev_b32_e32 v2, 22, v2
	v_add_u32_e32 v2, v1, v2
	v_ashrrev_i32_e32 v8, 10, v2
	v_mul_i32_i24_e32 v2, 0x400, v8
	v_sub_u32_e32 v1, v1, v2
	v_lshrrev_b32_e32 v2, 4, v1
	v_bitop3_b32 v1, v2, v1, 32 bitop3:0x6c
	v_ashrrev_i32_e32 v2, 31, v1
	v_lshrrev_b32_e32 v2, 26, v2
	v_add_u32_e32 v2, v1, v2
	v_ashrrev_i32_e32 v9, 6, v2
	v_and_b32_e32 v2, 0xc0, v2
	v_sub_u32_e32 v1, v1, v2
	v_ashrrev_i16_sdwa v1, v183, sext(v1) dst_sel:DWORD dst_unused:UNUSED_PAD src0_sel:DWORD src1_sel:BYTE_0
	v_bfe_i32 v11, v1, 0, 16
	v_bfe_i32 v1, v16, 27, 1
	v_lshrrev_b32_e32 v1, 22, v1
	v_add_u32_e32 v1, v0, v1
	v_and_b32_e32 v1, 0xfffffc00, v1
	v_sub_u32_e32 v0, v0, v1
	s_add_u32 s29, s62, 0x8e00000
	v_lshrrev_b32_e32 v1, 4, v0
	s_addc_u32 s30, s63, 0
	s_ashr_i32 s0, s27, 6
	v_bitop3_b32 v0, v1, v0, 32 bitop3:0x6c
	v_ashrrev_i32_e32 v2, 31, v16
	s_ashr_i32 s1, s27, 8
	s_lshl_b32 s31, s0, 10
	v_lshlrev_b32_e32 v3, 3, v8
	v_ashrrev_i32_e32 v1, 31, v0
	v_lshrrev_b32_e32 v2, 26, v2
	v_readlane_b32 s4, v252, 30
	v_readlane_b32 s6, v253, 15
	v_and_b32_e32 v3, 0xffff0, v3
	v_lshlrev_b32_e32 v4, 5, v8
	v_lshrrev_b32_e32 v1, 26, v1
	v_add_u32_e32 v2, v16, v2
	v_readlane_b32 s5, v252, 31
	s_add_u32 s4, s6, s4
	v_readlane_b32 s6, v253, 16
	v_add_u32_e32 v3, v9, v3
	v_and_b32_e32 v10, 32, v4
	v_add_u32_e32 v1, v0, v1
	v_ashrrev_i32_e32 v13, 6, v2
	s_addc_u32 s5, s6, s5
	v_readlane_b32 s6, v252, 34
	v_lshl_or_b32 v3, v3, 11, v10
	v_ashrrev_i32_e32 v12, 6, v1
	v_lshlrev_b32_e32 v2, 3, v13
	v_and_b32_e32 v1, 0xc0, v1
	v_readlane_b32 s7, v252, 35
	s_add_u32 s6, s29, s6
	v_add_lshl_u32 v160, v3, v11, 1
	v_and_b32_e32 v2, 0xffff0, v2
	v_lshlrev_b32_e32 v3, 5, v13
	v_sub_u32_e32 v0, v0, v1
	s_addc_u32 s7, s30, s7
	v_readlane_b32 s10, v251, 22
	v_add_u32_e32 v2, v12, v2
	v_and_b32_e32 v14, 32, v3
	v_ashrrev_i16_sdwa v0, v183, sext(v0) dst_sel:DWORD dst_unused:UNUSED_PAD src0_sel:DWORD src1_sel:BYTE_0
	v_readlane_b32 s11, v251, 23
	s_add_u32 s20, s6, s10
	v_lshl_or_b32 v2, v2, 11, v14
	v_bfe_i32 v15, v0, 0, 16
	s_addc_u32 s21, s7, s11
	s_add_i32 s33, s31, 0
	v_add_lshl_u32 v148, v2, v15, 1
	s_add_i32 m0, s33, 0x10000
	v_mov_b32_e32 v161, v149
	global_load_lds_dwordx4 v148, s[20:21]
	s_add_i32 m0, s33, 0x12000
	s_add_u32 s16, s4, s10
	global_load_lds_dwordx4 v160, s[20:21]
	s_addc_u32 s17, s5, s11
	s_mov_b32 m0, s33
	s_add_i32 s34, s33, 0x2000
	global_load_lds_dwordx4 v148, s[16:17]
	s_mov_b32 m0, s34
	s_add_u32 s4, s20, 0x80000
	global_load_lds_dwordx4 v160, s[16:17]
	s_addc_u32 s5, s21, 0
	s_add_i32 m0, s33, 0x14000
	v_lshl_add_u64 v[6:7], s[20:21], 0, v[148:149]
	global_load_lds_dwordx4 v148, s[4:5]
	s_add_i32 m0, s33, 0x16000
	v_lshl_add_u64 v[4:5], s[20:21], 0, v[160:161]
	global_load_lds_dwordx4 v160, s[4:5]
	s_add_u32 s4, s16, 0x80000
	s_addc_u32 s5, s17, 0
	s_add_i32 s35, s33, 0x4000
	s_mov_b32 m0, s35
	s_add_i32 s36, s33, 0x6000
	global_load_lds_dwordx4 v148, s[4:5]
	s_mov_b32 m0, s36
	v_lshl_add_u64 v[2:3], s[16:17], 0, v[148:149]
	global_load_lds_dwordx4 v160, s[4:5]
	s_cmp_lg_u32 s1, 1
	v_lshl_add_u64 v[0:1], s[16:17], 0, v[160:161]
	s_setprio 1
	s_cbranch_scc1 .LBB0_254
	s_barrier
	s_setprio 0
